# v88 + tile headers: the s_nop 0 that padded the removed VALU ballot (VALU-written mask now read only by SALU) dropped at 4 sites
# speedup vs baseline: 1.0000x; 1.0000x over previous
; template <class Epi, bool ALIGN_EPI = PG8_ALIGN, bool SP2 = PG8_SP2>
; __device__ __forceinline__ void gemm_phase(LAS uchar* lds, const Gemm g, const StaticOrder& S, const Epi& E) {
;     ...
;         const bool has_next = S.next(ui + 1, nxt);
;         const char* nA = has_next ? (const char*)g.A + (size_t)nxt.pm * tstepA : cA; const char* nB = has_next ? (const char*)g.Bt + (size_t)nxt.pn * tstepB : cB;
.LBB0_573:
	s_andn2_b64 s[6:7], exec, s[0:1]
	s_andn2_b64 vcc, exec, s[0:1]
	s_mov_b64 s[0:1], s[14:15]
	s_cbranch_vccnz .LBB0_575
	s_mul_i32 s0, s35, 0x308000
	s_mul_hi_i32 s1, s35, 0x308000
	s_add_u32 s0, s90, s0
	s_addc_u32 s1, s91, s1

; template <class Epi, bool ALIGN_EPI = PG8_ALIGN, bool SP2 = PG8_SP2>
; __device__ __forceinline__ void gemm_phase(LAS uchar* lds, const Gemm g, const StaticOrder& S, const Epi& E) {
;     ...
;         const bool has_next = S.next(ui + 1, nxt);
;         const char* nA = has_next ? (const char*)g.A + (size_t)nxt.pm * tstepA : cA; const char* nB = has_next ? (const char*)g.Bt + (size_t)nxt.pn * tstepB : cB;
.LBB0_832:
	s_andn2_b64 s[0:1], exec, s[4:5]
	s_andn2_b64 vcc, exec, s[4:5]
	s_mov_b64 s[4:5], s[12:13]
	s_cbranch_vccnz .LBB0_834
	s_mul_i32 s4, s31, 0x88000
	v_readlane_b32 s10, v254, 51
	s_mul_hi_i32 s5, s31, 0x88000
	v_readlane_b32 s11, v254, 52
	s_add_u32 s4, s10, s4
	s_addc_u32 s5, s11, s5

; template <class Epi, bool ALIGN_EPI = PG8_ALIGN, bool SP2 = PG8_SP2>
; __device__ __forceinline__ void gemm_phase(LAS uchar* lds, const Gemm g, const StaticOrder& S, const Epi& E) {
;     ...
;         const bool has_next = S.next(ui + 1, nxt);
;         const char* nA = has_next ? (const char*)g.A + (size_t)nxt.pm * tstepA : cA; const char* nB = has_next ? (const char*)g.Bt + (size_t)nxt.pn * tstepB : cB;
.LBB0_1045:
	s_andn2_b64 s[4:5], exec, s[0:1]
	s_andn2_b64 vcc, exec, s[0:1]
	s_mov_b64 s[0:1], s[12:13]
	s_cbranch_vccnz .LBB0_1047
	s_mul_i32 s0, s31, 0x88000
	v_readlane_b32 s40, v254, 4
	s_mul_hi_i32 s1, s31, 0x88000
	v_readlane_b32 s41, v254, 5
	s_add_u32 s0, s40, s0
	s_addc_u32 s1, s41, s1

; template <class Epi, bool ALIGN_EPI = PG8_ALIGN, bool SP2 = PG8_SP2>
; __device__ __forceinline__ void gemm_phase(LAS uchar* lds, const Gemm g, const StaticOrder& S, const Epi& E) {
;     ...
;         const bool has_next = S.next(ui + 1, nxt);
;         const char* nA = has_next ? (const char*)g.A + (size_t)nxt.pm * tstepA : cA; const char* nB = has_next ? (const char*)g.Bt + (size_t)nxt.pn * tstepB : cB;
.LBB0_1138:
	s_andn2_b64 s[0:1], exec, s[4:5]
	s_andn2_b64 vcc, exec, s[4:5]
	s_mov_b64 s[4:5], s[14:15]
	s_cbranch_vccnz .LBB0_1140
	s_mul_i32 s4, s35, 0x160000
	s_mul_hi_i32 s5, s35, 0x160000
	s_add_u32 s4, s90, s4
	s_addc_u32 s5, s91, s5
